# A0 GEMM K-loops: LDS-DMA pieces in scalar-base form with constant strides folded into per-lane 32-bit offsets (no per-piece 64-bit VALU address rebuild)
# speedup vs baseline: 1.0011x; 1.0011x over previous
.LBB0_169:
	v_add_u32_e32 v246, 0x80000, v130
	v_add_u32_e32 v247, 0x80000, v144
	v_add_u32_e32 v248, 0x100000, v144
	v_add_u32_e32 v249, 0x180000, v144
	v_add_u32_e32 v250, 0x80000, v128
	v_add_u32_e32 v251, 0x100000, v128
	v_add_u32_e32 v154, 0x180000, v128
	v_add_u32_e32 v155, 0x80, v144
	v_add_u32_e32 v174, 0x80080, v144
	v_add_u32_e32 v175, 0x100080, v144
	v_add_u32_e32 v176, 0x180080, v144
	v_add_u32_e32 v177, 0x80, v128
	v_add_u32_e32 v149, 0x80080, v128
	v_lshl_add_u32 v244, s80, 8, v133
	v_readlane_b32 s100, v253, 49
	v_ashrrev_i32_e32 v245, 31, v244
	v_readlane_b32 s101, v253, 50
	s_nop 1
	v_lshl_add_u64 v[244:245], v[244:245], 2, s[100:101]
	global_load_dword v236, v[244:245], off offset:64
	global_load_dword v237, v[244:245], off offset:128
	global_load_dword v238, v[244:245], off offset:192
	global_load_dword v239, v[244:245], off offset:512
	global_load_dword v240, v[244:245], off offset:576
	global_load_dword v241, v[244:245], off offset:640
	global_load_dword v242, v[244:245], off offset:704
	global_load_dword v243, v[244:245], off
	s_ashr_i32 s47, s46, 31
	s_lshl_b64 s[68:69], s[46:47], 21
	s_add_u32 s68, s39, s68
	s_addc_u32 s69, s43, s69
	s_and_b64 s[74:75], s[52:53], exec
	s_cselect_b32 s47, s69, s71
	s_cselect_b32 s74, s68, s70
	s_ashr_i32 s7, s6, 31
	s_lshl_b64 s[78:79], s[6:7], 21
	s_add_u32 s78, s37, s78
	s_addc_u32 s79, s38, s79
	s_and_b64 s[84:85], s[52:53], exec
	s_cselect_b32 s7, s79, s73
	s_cselect_b32 s75, s78, s72
	s_add_u32 s70, s70, 0x100080
	s_addc_u32 s71, s71, 0
	s_add_u32 s77, s72, 0x100
	v_mov_b32_e32 v0, 0
	s_addc_u32 s81, s73, 0
	s_mov_b32 s84, -2
	v_mov_b32_e32 v1, v0
	v_mov_b32_e32 v2, v0
	v_mov_b32_e32 v3, v0
	v_mov_b32_e32 v4, v0
	v_mov_b32_e32 v5, v0
	v_mov_b32_e32 v6, v0
	v_mov_b32_e32 v7, v0
	v_mov_b32_e32 v16, v0
	v_mov_b32_e32 v17, v0
	v_mov_b32_e32 v18, v0
	v_mov_b32_e32 v19, v0
	v_mov_b32_e32 v20, v0
	v_mov_b32_e32 v21, v0
	v_mov_b32_e32 v22, v0
	v_mov_b32_e32 v23, v0
	v_mov_b32_e32 v32, v0
	v_mov_b32_e32 v33, v0
	v_mov_b32_e32 v34, v0
	v_mov_b32_e32 v35, v0
	v_mov_b32_e32 v36, v0
	v_mov_b32_e32 v37, v0
	v_mov_b32_e32 v38, v0
	v_mov_b32_e32 v39, v0
	v_mov_b32_e32 v48, v0
	v_mov_b32_e32 v49, v0
	v_mov_b32_e32 v50, v0
	v_mov_b32_e32 v51, v0
	v_mov_b32_e32 v52, v0
	v_mov_b32_e32 v53, v0
	v_mov_b32_e32 v54, v0
	v_mov_b32_e32 v55, v0
	v_mov_b32_e32 v8, v0
	v_mov_b32_e32 v9, v0
	v_mov_b32_e32 v10, v0
	v_mov_b32_e32 v11, v0
	v_mov_b32_e32 v12, v0
	v_mov_b32_e32 v13, v0
	v_mov_b32_e32 v14, v0
	v_mov_b32_e32 v15, v0
	v_mov_b32_e32 v24, v0
	v_mov_b32_e32 v25, v0
	v_mov_b32_e32 v26, v0
	v_mov_b32_e32 v27, v0
	v_mov_b32_e32 v28, v0
	v_mov_b32_e32 v29, v0
	v_mov_b32_e32 v30, v0
	v_mov_b32_e32 v31, v0
	v_mov_b32_e32 v40, v0
	v_mov_b32_e32 v41, v0
	v_mov_b32_e32 v42, v0
	v_mov_b32_e32 v43, v0
	v_mov_b32_e32 v44, v0
	v_mov_b32_e32 v45, v0
	v_mov_b32_e32 v46, v0
	v_mov_b32_e32 v47, v0
	v_mov_b32_e32 v56, v0
	v_mov_b32_e32 v57, v0
	v_mov_b32_e32 v58, v0
	v_mov_b32_e32 v59, v0
	v_mov_b32_e32 v60, v0
	v_mov_b32_e32 v61, v0
	v_mov_b32_e32 v62, v0
	v_mov_b32_e32 v63, v0
	v_mov_b32_e32 v64, v0
	v_mov_b32_e32 v65, v0
	v_mov_b32_e32 v66, v0
	v_mov_b32_e32 v67, v0
	v_mov_b32_e32 v68, v0
	v_mov_b32_e32 v69, v0
	v_mov_b32_e32 v70, v0
	v_mov_b32_e32 v71, v0
	v_mov_b32_e32 v80, v0
	v_mov_b32_e32 v81, v0
	v_mov_b32_e32 v82, v0
	v_mov_b32_e32 v83, v0
	v_mov_b32_e32 v84, v0
	v_mov_b32_e32 v85, v0
	v_mov_b32_e32 v86, v0
	v_mov_b32_e32 v87, v0
	v_mov_b32_e32 v96, v0
	v_mov_b32_e32 v97, v0
	v_mov_b32_e32 v98, v0
	v_mov_b32_e32 v99, v0
	v_mov_b32_e32 v100, v0
	v_mov_b32_e32 v101, v0
	v_mov_b32_e32 v102, v0
	v_mov_b32_e32 v103, v0
	v_mov_b32_e32 v112, v0
	v_mov_b32_e32 v113, v0
	v_mov_b32_e32 v114, v0
	v_mov_b32_e32 v115, v0
	v_mov_b32_e32 v116, v0
	v_mov_b32_e32 v117, v0
	v_mov_b32_e32 v118, v0
	v_mov_b32_e32 v119, v0
	v_mov_b32_e32 v72, v0
	v_mov_b32_e32 v73, v0
	v_mov_b32_e32 v74, v0
	v_mov_b32_e32 v75, v0
	v_mov_b32_e32 v76, v0
	v_mov_b32_e32 v77, v0
	v_mov_b32_e32 v78, v0
	v_mov_b32_e32 v79, v0
	v_mov_b32_e32 v88, v0
	v_mov_b32_e32 v89, v0
	v_mov_b32_e32 v90, v0
	v_mov_b32_e32 v91, v0
	v_mov_b32_e32 v92, v0
	v_mov_b32_e32 v93, v0
	v_mov_b32_e32 v94, v0
	v_mov_b32_e32 v95, v0
	v_mov_b32_e32 v104, v0
	v_mov_b32_e32 v105, v0
	v_mov_b32_e32 v106, v0
	v_mov_b32_e32 v107, v0
	v_mov_b32_e32 v108, v0
	v_mov_b32_e32 v109, v0
	v_mov_b32_e32 v110, v0
	v_mov_b32_e32 v111, v0
	v_mov_b32_e32 v120, v0
	v_mov_b32_e32 v121, v0
	v_mov_b32_e32 v122, v0
	v_mov_b32_e32 v123, v0
	v_mov_b32_e32 v124, v0
	v_mov_b32_e32 v125, v0
	v_mov_b32_e32 v126, v0
	v_mov_b32_e32 v127, v0
.LBB0_170:
	s_add_u32 s36, s70, 0xfff00080
	s_addc_u32 s72, s71, -1
	s_add_i32 s85, 0, 0x10000
	s_cmp_eq_u32 s84, 60
	s_cselect_b32 s73, s47, s72
	s_cselect_b32 s72, s74, s36
	v_add_u32_e32 v132, s85, v137
	s_cselect_b32 s87, s7, s81
	s_cselect_b32 s86, s75, s77
	s_add_i32 s36, 0, 0x14000
	ds_read_b128 v[156:159], v132
	ds_read_b128 v[160:163], v132 offset:1024
	ds_read_b128 v[164:167], v132 offset:2048
	ds_read_b128 v[180:183], v132 offset:3072
	v_add_u32_e32 v132, s36, v137
	ds_read_b128 v[184:187], v132
	ds_read_b128 v[188:191], v132 offset:1024
	ds_read_b128 v[192:195], v132 offset:2048
	ds_read_b128 v[196:199], v132 offset:3072
	s_add_i32 m0, s18, 0xc000
	ds_read_b128 v[204:207], v141
	ds_read_b128 v[208:211], v141 offset:1024
	ds_read_b128 v[212:215], v141 offset:2048
	ds_read_b128 v[216:219], v141 offset:3072
	ds_read_b128 v[220:223], v141 offset:4096
	ds_read_b128 v[224:227], v141 offset:5120
	ds_read_b128 v[228:231], v141 offset:6144
	ds_read_b128 v[232:235], v141 offset:7168
	global_load_lds_dwordx4 v130, s[70:71]
	s_add_i32 m0, s18, 0xe000
	s_nop 0
	global_load_lds_dwordx4 v246, s[70:71]
	s_waitcnt vmcnt(8)
	s_waitcnt lgkmcnt(0)
	s_barrier
	s_setprio 1
	s_waitcnt lgkmcnt(0)
	v_mfma_f32_16x16x32_bf16 v[124:127], v[156:159], v[204:207], v[124:127]
	v_mfma_f32_16x16x32_bf16 v[120:123], v[164:167], v[204:207], v[120:123]
	v_mfma_f32_16x16x32_bf16 v[108:111], v[156:159], v[212:215], v[108:111]
	v_mfma_f32_16x16x32_bf16 v[104:107], v[164:167], v[212:215], v[104:107]
	v_mfma_f32_16x16x32_bf16 v[92:95], v[156:159], v[220:223], v[92:95]
	v_mfma_f32_16x16x32_bf16 v[88:91], v[164:167], v[220:223], v[88:91]
	v_mfma_f32_16x16x32_bf16 v[76:79], v[156:159], v[228:231], v[76:79]
	v_mfma_f32_16x16x32_bf16 v[72:75], v[164:167], v[228:231], v[72:75]
	v_mfma_f32_16x16x32_bf16 v[124:127], v[160:163], v[208:211], v[124:127]
	v_mfma_f32_16x16x32_bf16 v[120:123], v[180:183], v[208:211], v[120:123]
	v_mfma_f32_16x16x32_bf16 v[108:111], v[160:163], v[216:219], v[108:111]
	v_mfma_f32_16x16x32_bf16 v[104:107], v[180:183], v[216:219], v[104:107]
	v_mfma_f32_16x16x32_bf16 v[92:95], v[160:163], v[224:227], v[92:95]
	v_mfma_f32_16x16x32_bf16 v[88:91], v[180:183], v[224:227], v[88:91]
	v_mfma_f32_16x16x32_bf16 v[76:79], v[160:163], v[232:235], v[76:79]
	v_mfma_f32_16x16x32_bf16 v[72:75], v[180:183], v[232:235], v[72:75]
	s_setprio 0
	s_setprio 1
	v_mfma_f32_16x16x32_bf16 v[116:119], v[184:187], v[204:207], v[116:119]
	v_mfma_f32_16x16x32_bf16 v[112:115], v[192:195], v[204:207], v[112:115]
	v_mfma_f32_16x16x32_bf16 v[100:103], v[184:187], v[212:215], v[100:103]
	v_mfma_f32_16x16x32_bf16 v[96:99], v[192:195], v[212:215], v[96:99]
	v_mfma_f32_16x16x32_bf16 v[84:87], v[184:187], v[220:223], v[84:87]
	v_mfma_f32_16x16x32_bf16 v[80:83], v[192:195], v[220:223], v[80:83]
	v_mfma_f32_16x16x32_bf16 v[68:71], v[184:187], v[228:231], v[68:71]
	v_mfma_f32_16x16x32_bf16 v[64:67], v[192:195], v[228:231], v[64:67]
	v_mfma_f32_16x16x32_bf16 v[116:119], v[188:191], v[208:211], v[116:119]
	v_mfma_f32_16x16x32_bf16 v[112:115], v[196:199], v[208:211], v[112:115]
	v_mfma_f32_16x16x32_bf16 v[100:103], v[188:191], v[216:219], v[100:103]
	v_mfma_f32_16x16x32_bf16 v[96:99], v[196:199], v[216:219], v[96:99]
	v_mfma_f32_16x16x32_bf16 v[84:87], v[188:191], v[224:227], v[84:87]
	v_mfma_f32_16x16x32_bf16 v[80:83], v[196:199], v[224:227], v[80:83]
	v_mfma_f32_16x16x32_bf16 v[68:71], v[188:191], v[232:235], v[68:71]
	v_mfma_f32_16x16x32_bf16 v[64:67], v[196:199], v[232:235], v[64:67]
	s_setprio 0
	s_barrier
	s_add_i32 s85, s85, s17
	s_mov_b32 m0, s85
	ds_read_b128 v[204:207], v141 offset:16384
	ds_read_b128 v[208:211], v141 offset:17408
	ds_read_b128 v[212:215], v141 offset:18432
	ds_read_b128 v[216:219], v141 offset:19456
	ds_read_b128 v[220:223], v141 offset:20480
	ds_read_b128 v[224:227], v141 offset:21504
	ds_read_b128 v[228:231], v141 offset:22528
	ds_read_b128 v[232:235], v141 offset:23552
	global_load_lds_dwordx4 v144, s[86:87]
	s_add_i32 m0, s85, 0x2000
	s_add_i32 s36, s36, s17
	global_load_lds_dwordx4 v247, s[86:87]
	s_mov_b32 m0, s36
	s_nop 0
	global_load_lds_dwordx4 v248, s[86:87]
	s_add_i32 m0, s36, 0x2000
	s_nop 0
	global_load_lds_dwordx4 v249, s[86:87]
	s_mov_b32 m0, s18
	s_nop 0
	global_load_lds_dwordx4 v128, s[72:73]
	s_mov_b32 m0, s19
	s_nop 0
	global_load_lds_dwordx4 v250, s[72:73]
	s_waitcnt vmcnt(8)
	s_waitcnt lgkmcnt(0)
	s_barrier
	s_setprio 1
	s_waitcnt lgkmcnt(0)
	v_mfma_f32_16x16x32_bf16 v[60:63], v[156:159], v[204:207], v[60:63]
	v_mfma_f32_16x16x32_bf16 v[56:59], v[164:167], v[204:207], v[56:59]
	v_mfma_f32_16x16x32_bf16 v[44:47], v[156:159], v[212:215], v[44:47]
	v_mfma_f32_16x16x32_bf16 v[40:43], v[164:167], v[212:215], v[40:43]
	v_mfma_f32_16x16x32_bf16 v[28:31], v[156:159], v[220:223], v[28:31]
	v_mfma_f32_16x16x32_bf16 v[24:27], v[164:167], v[220:223], v[24:27]
	v_mfma_f32_16x16x32_bf16 v[12:15], v[156:159], v[228:231], v[12:15]
	v_mfma_f32_16x16x32_bf16 v[8:11], v[164:167], v[228:231], v[8:11]
	v_mfma_f32_16x16x32_bf16 v[60:63], v[160:163], v[208:211], v[60:63]
	v_mfma_f32_16x16x32_bf16 v[56:59], v[180:183], v[208:211], v[56:59]
	v_mfma_f32_16x16x32_bf16 v[44:47], v[160:163], v[216:219], v[44:47]
	v_mfma_f32_16x16x32_bf16 v[40:43], v[180:183], v[216:219], v[40:43]
	v_mfma_f32_16x16x32_bf16 v[28:31], v[160:163], v[224:227], v[28:31]
	v_mfma_f32_16x16x32_bf16 v[24:27], v[180:183], v[224:227], v[24:27]
	v_mfma_f32_16x16x32_bf16 v[12:15], v[160:163], v[232:235], v[12:15]
	v_mfma_f32_16x16x32_bf16 v[8:11], v[180:183], v[232:235], v[8:11]
	s_setprio 0
	s_setprio 1
	v_mfma_f32_16x16x32_bf16 v[52:55], v[184:187], v[204:207], v[52:55]
	v_mfma_f32_16x16x32_bf16 v[48:51], v[192:195], v[204:207], v[48:51]
	v_mfma_f32_16x16x32_bf16 v[36:39], v[184:187], v[212:215], v[36:39]
	v_mfma_f32_16x16x32_bf16 v[32:35], v[192:195], v[212:215], v[32:35]
	v_mfma_f32_16x16x32_bf16 v[20:23], v[184:187], v[220:223], v[20:23]
	v_mfma_f32_16x16x32_bf16 v[16:19], v[192:195], v[220:223], v[16:19]
	v_mfma_f32_16x16x32_bf16 v[4:7], v[184:187], v[228:231], v[4:7]
	v_mfma_f32_16x16x32_bf16 v[0:3], v[192:195], v[228:231], v[0:3]
	v_mfma_f32_16x16x32_bf16 v[52:55], v[188:191], v[208:211], v[52:55]
	v_mfma_f32_16x16x32_bf16 v[48:51], v[196:199], v[208:211], v[48:51]
	v_mfma_f32_16x16x32_bf16 v[36:39], v[188:191], v[216:219], v[36:39]
	v_mfma_f32_16x16x32_bf16 v[32:35], v[196:199], v[216:219], v[32:35]
	v_mfma_f32_16x16x32_bf16 v[20:23], v[188:191], v[224:227], v[20:23]
	v_mfma_f32_16x16x32_bf16 v[16:19], v[196:199], v[224:227], v[16:19]
	v_mfma_f32_16x16x32_bf16 v[4:7], v[188:191], v[232:235], v[4:7]
	v_mfma_f32_16x16x32_bf16 v[0:3], v[196:199], v[232:235], v[0:3]
	s_setprio 0
	s_barrier
	s_add_i32 s36, 0, 0x18000
	v_add_u32_e32 v132, s36, v137
	s_add_i32 s100, 0, 0x1c000
	ds_read_b128 v[156:159], v132
	ds_read_b128 v[160:163], v132 offset:1024
	ds_read_b128 v[164:167], v132 offset:2048
	ds_read_b128 v[180:183], v132 offset:3072
	v_add_u32_e32 v132, s100, v137
	ds_read_b128 v[184:187], v132
	ds_read_b128 v[188:191], v132 offset:1024
	ds_read_b128 v[192:195], v132 offset:2048
	ds_read_b128 v[196:199], v132 offset:3072
	s_mov_b32 m0, s20
	ds_read_b128 v[204:207], v141 offset:32768
	ds_read_b128 v[208:211], v141 offset:33792
	ds_read_b128 v[212:215], v141 offset:34816
	ds_read_b128 v[216:219], v141 offset:35840
	ds_read_b128 v[220:223], v141 offset:36864
	ds_read_b128 v[224:227], v141 offset:37888
	ds_read_b128 v[228:231], v141 offset:38912
	ds_read_b128 v[232:235], v141 offset:39936
	global_load_lds_dwordx4 v251, s[72:73]
	s_mov_b32 m0, s21
	s_nop 0
	global_load_lds_dwordx4 v154, s[72:73]
	s_waitcnt vmcnt(8)
	s_waitcnt lgkmcnt(0)
	s_barrier
	s_setprio 1
	s_waitcnt lgkmcnt(0)
	v_mfma_f32_16x16x32_bf16 v[124:127], v[156:159], v[204:207], v[124:127]
	v_mfma_f32_16x16x32_bf16 v[120:123], v[164:167], v[204:207], v[120:123]
	v_mfma_f32_16x16x32_bf16 v[108:111], v[156:159], v[212:215], v[108:111]
	v_mfma_f32_16x16x32_bf16 v[104:107], v[164:167], v[212:215], v[104:107]
	v_mfma_f32_16x16x32_bf16 v[92:95], v[156:159], v[220:223], v[92:95]
	v_mfma_f32_16x16x32_bf16 v[88:91], v[164:167], v[220:223], v[88:91]
	v_mfma_f32_16x16x32_bf16 v[76:79], v[156:159], v[228:231], v[76:79]
	v_mfma_f32_16x16x32_bf16 v[72:75], v[164:167], v[228:231], v[72:75]
	v_mfma_f32_16x16x32_bf16 v[124:127], v[160:163], v[208:211], v[124:127]
	v_mfma_f32_16x16x32_bf16 v[120:123], v[180:183], v[208:211], v[120:123]
	v_mfma_f32_16x16x32_bf16 v[108:111], v[160:163], v[216:219], v[108:111]
	v_mfma_f32_16x16x32_bf16 v[104:107], v[180:183], v[216:219], v[104:107]
	v_mfma_f32_16x16x32_bf16 v[92:95], v[160:163], v[224:227], v[92:95]
	v_mfma_f32_16x16x32_bf16 v[88:91], v[180:183], v[224:227], v[88:91]
	v_mfma_f32_16x16x32_bf16 v[76:79], v[160:163], v[232:235], v[76:79]
	v_mfma_f32_16x16x32_bf16 v[72:75], v[180:183], v[232:235], v[72:75]
	s_setprio 0
	s_setprio 1
	v_mfma_f32_16x16x32_bf16 v[116:119], v[184:187], v[204:207], v[116:119]
	v_mfma_f32_16x16x32_bf16 v[112:115], v[192:195], v[204:207], v[112:115]
	v_mfma_f32_16x16x32_bf16 v[100:103], v[184:187], v[212:215], v[100:103]
	v_mfma_f32_16x16x32_bf16 v[96:99], v[192:195], v[212:215], v[96:99]
	v_mfma_f32_16x16x32_bf16 v[84:87], v[184:187], v[220:223], v[84:87]
	v_mfma_f32_16x16x32_bf16 v[80:83], v[192:195], v[220:223], v[80:83]
	v_mfma_f32_16x16x32_bf16 v[68:71], v[184:187], v[228:231], v[68:71]
	v_mfma_f32_16x16x32_bf16 v[64:67], v[192:195], v[228:231], v[64:67]
	v_mfma_f32_16x16x32_bf16 v[116:119], v[188:191], v[208:211], v[116:119]
	v_mfma_f32_16x16x32_bf16 v[112:115], v[196:199], v[208:211], v[112:115]
	v_mfma_f32_16x16x32_bf16 v[100:103], v[188:191], v[216:219], v[100:103]
	v_mfma_f32_16x16x32_bf16 v[96:99], v[196:199], v[216:219], v[96:99]
	v_mfma_f32_16x16x32_bf16 v[84:87], v[188:191], v[224:227], v[84:87]
	v_mfma_f32_16x16x32_bf16 v[80:83], v[196:199], v[224:227], v[80:83]
	v_mfma_f32_16x16x32_bf16 v[68:71], v[188:191], v[232:235], v[68:71]
	v_mfma_f32_16x16x32_bf16 v[64:67], v[196:199], v[232:235], v[64:67]
	s_setprio 0
	s_barrier
	s_add_i32 s36, s36, s17
	s_mov_b32 m0, s36
	ds_read_b128 v[204:207], v141 offset:49152
	ds_read_b128 v[208:211], v141 offset:50176
	ds_read_b128 v[212:215], v141 offset:51200
	ds_read_b128 v[216:219], v141 offset:52224
	ds_read_b128 v[220:223], v141 offset:53248
	ds_read_b128 v[224:227], v141 offset:54272
	ds_read_b128 v[228:231], v141 offset:55296
	ds_read_b128 v[232:235], v141 offset:56320
	global_load_lds_dwordx4 v155, s[86:87]
	s_add_i32 m0, s36, 0x2000
	s_add_i32 s36, s100, s17
	global_load_lds_dwordx4 v174, s[86:87]
	s_mov_b32 m0, s36
	s_nop 0
	global_load_lds_dwordx4 v175, s[86:87]
	s_add_i32 m0, s36, 0x2000
	s_nop 0
	global_load_lds_dwordx4 v176, s[86:87]
	s_mov_b32 m0, s22
	s_nop 0
	global_load_lds_dwordx4 v177, s[72:73]
	s_mov_b32 m0, s23
	s_nop 0
	global_load_lds_dwordx4 v149, s[72:73]
	s_waitcnt vmcnt(8)
	s_waitcnt lgkmcnt(0)
	s_barrier
	s_setprio 1
	s_waitcnt lgkmcnt(0)
	v_mfma_f32_16x16x32_bf16 v[60:63], v[156:159], v[204:207], v[60:63]
	v_mfma_f32_16x16x32_bf16 v[56:59], v[164:167], v[204:207], v[56:59]
	v_mfma_f32_16x16x32_bf16 v[44:47], v[156:159], v[212:215], v[44:47]
	v_mfma_f32_16x16x32_bf16 v[40:43], v[164:167], v[212:215], v[40:43]
	v_mfma_f32_16x16x32_bf16 v[28:31], v[156:159], v[220:223], v[28:31]
	v_mfma_f32_16x16x32_bf16 v[24:27], v[164:167], v[220:223], v[24:27]
	v_mfma_f32_16x16x32_bf16 v[12:15], v[156:159], v[228:231], v[12:15]
	v_mfma_f32_16x16x32_bf16 v[8:11], v[164:167], v[228:231], v[8:11]
	v_mfma_f32_16x16x32_bf16 v[60:63], v[160:163], v[208:211], v[60:63]
	v_mfma_f32_16x16x32_bf16 v[56:59], v[180:183], v[208:211], v[56:59]
	v_mfma_f32_16x16x32_bf16 v[44:47], v[160:163], v[216:219], v[44:47]
	v_mfma_f32_16x16x32_bf16 v[40:43], v[180:183], v[216:219], v[40:43]
	v_mfma_f32_16x16x32_bf16 v[28:31], v[160:163], v[224:227], v[28:31]
	v_mfma_f32_16x16x32_bf16 v[24:27], v[180:183], v[224:227], v[24:27]
	v_mfma_f32_16x16x32_bf16 v[12:15], v[160:163], v[232:235], v[12:15]
	v_mfma_f32_16x16x32_bf16 v[8:11], v[180:183], v[232:235], v[8:11]
	s_setprio 0
	s_setprio 1
	v_mfma_f32_16x16x32_bf16 v[52:55], v[184:187], v[204:207], v[52:55]
	v_mfma_f32_16x16x32_bf16 v[48:51], v[192:195], v[204:207], v[48:51]
	v_mfma_f32_16x16x32_bf16 v[36:39], v[184:187], v[212:215], v[36:39]
	v_mfma_f32_16x16x32_bf16 v[32:35], v[192:195], v[212:215], v[32:35]
	v_mfma_f32_16x16x32_bf16 v[20:23], v[184:187], v[220:223], v[20:23]
	v_mfma_f32_16x16x32_bf16 v[16:19], v[192:195], v[220:223], v[16:19]
	v_mfma_f32_16x16x32_bf16 v[4:7], v[184:187], v[228:231], v[4:7]
	v_mfma_f32_16x16x32_bf16 v[0:3], v[192:195], v[228:231], v[0:3]
	v_mfma_f32_16x16x32_bf16 v[52:55], v[188:191], v[208:211], v[52:55]
	v_mfma_f32_16x16x32_bf16 v[48:51], v[196:199], v[208:211], v[48:51]
	v_mfma_f32_16x16x32_bf16 v[36:39], v[188:191], v[216:219], v[36:39]
	v_mfma_f32_16x16x32_bf16 v[32:35], v[196:199], v[216:219], v[32:35]
	v_mfma_f32_16x16x32_bf16 v[20:23], v[188:191], v[224:227], v[20:23]
	v_mfma_f32_16x16x32_bf16 v[16:19], v[196:199], v[224:227], v[16:19]
	v_mfma_f32_16x16x32_bf16 v[4:7], v[188:191], v[232:235], v[4:7]
	v_mfma_f32_16x16x32_bf16 v[0:3], v[196:199], v[232:235], v[0:3]
	s_setprio 0
	s_barrier
	s_add_i32 s84, s84, 2
	s_add_u32 s70, s70, 0x100
	s_addc_u32 s71, s71, 0
	s_add_u32 s77, s77, 0x100
	s_addc_u32 s81, s81, 0
	s_cmp_gt_u32 s84, 61
	s_cbranch_scc0 .LBB0_170
	s_and_b64 vcc, exec, s[4:5]
	s_movk_i32 s77, 0x7fff
	s_cbranch_vccz .LBB0_173
	s_barrier

.LBB0_332:
	v_add_u32_e32 v246, 0x80000, v130
	v_add_u32_e32 v247, 0x80000, v144
	v_add_u32_e32 v248, 0x100000, v144
	v_add_u32_e32 v249, 0x180000, v144
	v_add_u32_e32 v250, 0x80000, v128
	v_add_u32_e32 v251, 0x100000, v128
	v_add_u32_e32 v154, 0x180000, v128
	v_add_u32_e32 v155, 0x80, v144
	v_add_u32_e32 v174, 0x80080, v144
	v_add_u32_e32 v175, 0x100080, v144
	v_add_u32_e32 v176, 0x180080, v144
	v_add_u32_e32 v177, 0x80, v128
	v_add_u32_e32 v149, 0x80080, v128
	v_lshl_add_u32 v244, s84, 8, v133
	v_readlane_b32 s100, v253, 49
	v_ashrrev_i32_e32 v245, 31, v244
	v_readlane_b32 s101, v253, 50
	s_nop 1
	v_lshl_add_u64 v[244:245], v[244:245], 2, s[100:101]
	global_load_dword v236, v[244:245], off offset:64
	global_load_dword v237, v[244:245], off offset:128
	global_load_dword v238, v[244:245], off offset:192
	global_load_dword v239, v[244:245], off offset:512
	global_load_dword v240, v[244:245], off offset:576
	global_load_dword v241, v[244:245], off offset:640
	global_load_dword v242, v[244:245], off offset:704
	global_load_dword v243, v[244:245], off
	s_ashr_i32 s47, s46, 31
	s_lshl_b64 s[68:69], s[46:47], 21
	s_add_u32 s68, s39, s68
	s_addc_u32 s69, s43, s69
	s_and_b64 s[74:75], s[52:53], exec
	s_cselect_b32 s42, s69, s71
	s_cselect_b32 s47, s68, s70
	s_ashr_i32 s7, s6, 31
	s_lshl_b64 s[74:75], s[6:7], 21
	s_add_u32 s78, s37, s74
	s_addc_u32 s79, s38, s75
	s_and_b64 s[74:75], s[52:53], exec
	s_cselect_b32 s7, s79, s73
	s_cselect_b32 s74, s78, s72
	s_add_u32 s70, s70, 0x100080
	s_addc_u32 s71, s71, 0
	s_add_u32 s75, s72, 0x100
	v_mov_b32_e32 v0, 0
	s_addc_u32 s77, s73, 0
	s_mov_b32 s81, -2
	v_mov_b32_e32 v1, v0
	v_mov_b32_e32 v2, v0
	v_mov_b32_e32 v3, v0
	v_mov_b32_e32 v4, v0
	v_mov_b32_e32 v5, v0
	v_mov_b32_e32 v6, v0
	v_mov_b32_e32 v7, v0
	v_mov_b32_e32 v16, v0
	v_mov_b32_e32 v17, v0
	v_mov_b32_e32 v18, v0
	v_mov_b32_e32 v19, v0
	v_mov_b32_e32 v20, v0
	v_mov_b32_e32 v21, v0
	v_mov_b32_e32 v22, v0
	v_mov_b32_e32 v23, v0
	v_mov_b32_e32 v32, v0
	v_mov_b32_e32 v33, v0
	v_mov_b32_e32 v34, v0
	v_mov_b32_e32 v35, v0
	v_mov_b32_e32 v36, v0
	v_mov_b32_e32 v37, v0
	v_mov_b32_e32 v38, v0
	v_mov_b32_e32 v39, v0
	v_mov_b32_e32 v48, v0
	v_mov_b32_e32 v49, v0
	v_mov_b32_e32 v50, v0
	v_mov_b32_e32 v51, v0
	v_mov_b32_e32 v52, v0
	v_mov_b32_e32 v53, v0
	v_mov_b32_e32 v54, v0
	v_mov_b32_e32 v55, v0
	v_mov_b32_e32 v8, v0
	v_mov_b32_e32 v9, v0
	v_mov_b32_e32 v10, v0
	v_mov_b32_e32 v11, v0
	v_mov_b32_e32 v12, v0
	v_mov_b32_e32 v13, v0
	v_mov_b32_e32 v14, v0
	v_mov_b32_e32 v15, v0
	v_mov_b32_e32 v24, v0
	v_mov_b32_e32 v25, v0
	v_mov_b32_e32 v26, v0
	v_mov_b32_e32 v27, v0
	v_mov_b32_e32 v28, v0
	v_mov_b32_e32 v29, v0
	v_mov_b32_e32 v30, v0
	v_mov_b32_e32 v31, v0
	v_mov_b32_e32 v40, v0
	v_mov_b32_e32 v41, v0
	v_mov_b32_e32 v42, v0
	v_mov_b32_e32 v43, v0
	v_mov_b32_e32 v44, v0
	v_mov_b32_e32 v45, v0
	v_mov_b32_e32 v46, v0
	v_mov_b32_e32 v47, v0
	v_mov_b32_e32 v56, v0
	v_mov_b32_e32 v57, v0
	v_mov_b32_e32 v58, v0
	v_mov_b32_e32 v59, v0
	v_mov_b32_e32 v60, v0
	v_mov_b32_e32 v61, v0
	v_mov_b32_e32 v62, v0
	v_mov_b32_e32 v63, v0
	v_mov_b32_e32 v64, v0
	v_mov_b32_e32 v65, v0
	v_mov_b32_e32 v66, v0
	v_mov_b32_e32 v67, v0
	v_mov_b32_e32 v68, v0
	v_mov_b32_e32 v69, v0
	v_mov_b32_e32 v70, v0
	v_mov_b32_e32 v71, v0
	v_mov_b32_e32 v80, v0
	v_mov_b32_e32 v81, v0
	v_mov_b32_e32 v82, v0
	v_mov_b32_e32 v83, v0
	v_mov_b32_e32 v84, v0
	v_mov_b32_e32 v85, v0
	v_mov_b32_e32 v86, v0
	v_mov_b32_e32 v87, v0
	v_mov_b32_e32 v96, v0
	v_mov_b32_e32 v97, v0
	v_mov_b32_e32 v98, v0
	v_mov_b32_e32 v99, v0
	v_mov_b32_e32 v100, v0
	v_mov_b32_e32 v101, v0
	v_mov_b32_e32 v102, v0
	v_mov_b32_e32 v103, v0
	v_mov_b32_e32 v112, v0
	v_mov_b32_e32 v113, v0
	v_mov_b32_e32 v114, v0
	v_mov_b32_e32 v115, v0
	v_mov_b32_e32 v116, v0
	v_mov_b32_e32 v117, v0
	v_mov_b32_e32 v118, v0
	v_mov_b32_e32 v119, v0
	v_mov_b32_e32 v72, v0
	v_mov_b32_e32 v73, v0
	v_mov_b32_e32 v74, v0
	v_mov_b32_e32 v75, v0
	v_mov_b32_e32 v76, v0
	v_mov_b32_e32 v77, v0
	v_mov_b32_e32 v78, v0
	v_mov_b32_e32 v79, v0
	v_mov_b32_e32 v88, v0
	v_mov_b32_e32 v89, v0
	v_mov_b32_e32 v90, v0
	v_mov_b32_e32 v91, v0
	v_mov_b32_e32 v92, v0
	v_mov_b32_e32 v93, v0
	v_mov_b32_e32 v94, v0
	v_mov_b32_e32 v95, v0
	v_mov_b32_e32 v104, v0
	v_mov_b32_e32 v105, v0
	v_mov_b32_e32 v106, v0
	v_mov_b32_e32 v107, v0
	v_mov_b32_e32 v108, v0
	v_mov_b32_e32 v109, v0
	v_mov_b32_e32 v110, v0
	v_mov_b32_e32 v111, v0
	v_mov_b32_e32 v120, v0
	v_mov_b32_e32 v121, v0
	v_mov_b32_e32 v122, v0
	v_mov_b32_e32 v123, v0
	v_mov_b32_e32 v124, v0
	v_mov_b32_e32 v125, v0
	v_mov_b32_e32 v126, v0
	v_mov_b32_e32 v127, v0
.LBB0_333:
	s_add_u32 s36, s70, 0xfff00080
	s_addc_u32 s72, s71, -1
	s_add_i32 s85, 0, 0x10000
	s_cmp_eq_u32 s81, 60
	s_cselect_b32 s73, s42, s72
	s_cselect_b32 s72, s47, s36
	v_add_u32_e32 v132, s85, v137
	s_cselect_b32 s87, s7, s77
	s_cselect_b32 s86, s74, s75
	s_add_i32 s36, 0, 0x14000
	ds_read_b128 v[156:159], v132
	ds_read_b128 v[160:163], v132 offset:1024
	ds_read_b128 v[164:167], v132 offset:2048
	ds_read_b128 v[180:183], v132 offset:3072
	v_add_u32_e32 v132, s36, v137
	ds_read_b128 v[184:187], v132
	ds_read_b128 v[188:191], v132 offset:1024
	ds_read_b128 v[192:195], v132 offset:2048
	ds_read_b128 v[196:199], v132 offset:3072
	s_add_i32 m0, s18, 0xc000
	ds_read_b128 v[204:207], v141
	ds_read_b128 v[208:211], v141 offset:1024
	ds_read_b128 v[212:215], v141 offset:2048
	ds_read_b128 v[216:219], v141 offset:3072
	ds_read_b128 v[220:223], v141 offset:4096
	ds_read_b128 v[224:227], v141 offset:5120
	ds_read_b128 v[228:231], v141 offset:6144
	ds_read_b128 v[232:235], v141 offset:7168
	global_load_lds_dwordx4 v130, s[70:71]
	s_add_i32 m0, s18, 0xe000
	s_nop 0
	global_load_lds_dwordx4 v246, s[70:71]
	s_waitcnt vmcnt(8)
	s_waitcnt lgkmcnt(0)
	s_barrier
	s_setprio 1
	s_waitcnt lgkmcnt(0)
	v_mfma_f32_16x16x32_bf16 v[124:127], v[156:159], v[204:207], v[124:127]
	v_mfma_f32_16x16x32_bf16 v[120:123], v[164:167], v[204:207], v[120:123]
	v_mfma_f32_16x16x32_bf16 v[108:111], v[156:159], v[212:215], v[108:111]
	v_mfma_f32_16x16x32_bf16 v[104:107], v[164:167], v[212:215], v[104:107]
	v_mfma_f32_16x16x32_bf16 v[92:95], v[156:159], v[220:223], v[92:95]
	v_mfma_f32_16x16x32_bf16 v[88:91], v[164:167], v[220:223], v[88:91]
	v_mfma_f32_16x16x32_bf16 v[76:79], v[156:159], v[228:231], v[76:79]
	v_mfma_f32_16x16x32_bf16 v[72:75], v[164:167], v[228:231], v[72:75]
	v_mfma_f32_16x16x32_bf16 v[124:127], v[160:163], v[208:211], v[124:127]
	v_mfma_f32_16x16x32_bf16 v[120:123], v[180:183], v[208:211], v[120:123]
	v_mfma_f32_16x16x32_bf16 v[108:111], v[160:163], v[216:219], v[108:111]
	v_mfma_f32_16x16x32_bf16 v[104:107], v[180:183], v[216:219], v[104:107]
	v_mfma_f32_16x16x32_bf16 v[92:95], v[160:163], v[224:227], v[92:95]
	v_mfma_f32_16x16x32_bf16 v[88:91], v[180:183], v[224:227], v[88:91]
	v_mfma_f32_16x16x32_bf16 v[76:79], v[160:163], v[232:235], v[76:79]
	v_mfma_f32_16x16x32_bf16 v[72:75], v[180:183], v[232:235], v[72:75]
	s_setprio 0
	s_setprio 1
	v_mfma_f32_16x16x32_bf16 v[116:119], v[184:187], v[204:207], v[116:119]
	v_mfma_f32_16x16x32_bf16 v[112:115], v[192:195], v[204:207], v[112:115]
	v_mfma_f32_16x16x32_bf16 v[100:103], v[184:187], v[212:215], v[100:103]
	v_mfma_f32_16x16x32_bf16 v[96:99], v[192:195], v[212:215], v[96:99]
	v_mfma_f32_16x16x32_bf16 v[84:87], v[184:187], v[220:223], v[84:87]
	v_mfma_f32_16x16x32_bf16 v[80:83], v[192:195], v[220:223], v[80:83]
	v_mfma_f32_16x16x32_bf16 v[68:71], v[184:187], v[228:231], v[68:71]
	v_mfma_f32_16x16x32_bf16 v[64:67], v[192:195], v[228:231], v[64:67]
	v_mfma_f32_16x16x32_bf16 v[116:119], v[188:191], v[208:211], v[116:119]
	v_mfma_f32_16x16x32_bf16 v[112:115], v[196:199], v[208:211], v[112:115]
	v_mfma_f32_16x16x32_bf16 v[100:103], v[188:191], v[216:219], v[100:103]
	v_mfma_f32_16x16x32_bf16 v[96:99], v[196:199], v[216:219], v[96:99]
	v_mfma_f32_16x16x32_bf16 v[84:87], v[188:191], v[224:227], v[84:87]
	v_mfma_f32_16x16x32_bf16 v[80:83], v[196:199], v[224:227], v[80:83]
	v_mfma_f32_16x16x32_bf16 v[68:71], v[188:191], v[232:235], v[68:71]
	v_mfma_f32_16x16x32_bf16 v[64:67], v[196:199], v[232:235], v[64:67]
	s_setprio 0
	s_barrier
	s_add_i32 s85, s85, s17
	s_mov_b32 m0, s85
	ds_read_b128 v[204:207], v141 offset:16384
	ds_read_b128 v[208:211], v141 offset:17408
	ds_read_b128 v[212:215], v141 offset:18432
	ds_read_b128 v[216:219], v141 offset:19456
	ds_read_b128 v[220:223], v141 offset:20480
	ds_read_b128 v[224:227], v141 offset:21504
	ds_read_b128 v[228:231], v141 offset:22528
	ds_read_b128 v[232:235], v141 offset:23552
	global_load_lds_dwordx4 v144, s[86:87]
	s_add_i32 m0, s85, 0x2000
	s_add_i32 s36, s36, s17
	global_load_lds_dwordx4 v247, s[86:87]
	s_mov_b32 m0, s36
	s_nop 0
	global_load_lds_dwordx4 v248, s[86:87]
	s_add_i32 m0, s36, 0x2000
	s_nop 0
	global_load_lds_dwordx4 v249, s[86:87]
	s_mov_b32 m0, s18
	s_nop 0
	global_load_lds_dwordx4 v128, s[72:73]
	s_mov_b32 m0, s19
	s_nop 0
	global_load_lds_dwordx4 v250, s[72:73]
	s_waitcnt vmcnt(8)
	s_waitcnt lgkmcnt(0)
	s_barrier
	s_setprio 1
	s_waitcnt lgkmcnt(0)
	v_mfma_f32_16x16x32_bf16 v[60:63], v[156:159], v[204:207], v[60:63]
	v_mfma_f32_16x16x32_bf16 v[56:59], v[164:167], v[204:207], v[56:59]
	v_mfma_f32_16x16x32_bf16 v[44:47], v[156:159], v[212:215], v[44:47]
	v_mfma_f32_16x16x32_bf16 v[40:43], v[164:167], v[212:215], v[40:43]
	v_mfma_f32_16x16x32_bf16 v[28:31], v[156:159], v[220:223], v[28:31]
	v_mfma_f32_16x16x32_bf16 v[24:27], v[164:167], v[220:223], v[24:27]
	v_mfma_f32_16x16x32_bf16 v[12:15], v[156:159], v[228:231], v[12:15]
	v_mfma_f32_16x16x32_bf16 v[8:11], v[164:167], v[228:231], v[8:11]
	v_mfma_f32_16x16x32_bf16 v[60:63], v[160:163], v[208:211], v[60:63]
	v_mfma_f32_16x16x32_bf16 v[56:59], v[180:183], v[208:211], v[56:59]
	v_mfma_f32_16x16x32_bf16 v[44:47], v[160:163], v[216:219], v[44:47]
	v_mfma_f32_16x16x32_bf16 v[40:43], v[180:183], v[216:219], v[40:43]
	v_mfma_f32_16x16x32_bf16 v[28:31], v[160:163], v[224:227], v[28:31]
	v_mfma_f32_16x16x32_bf16 v[24:27], v[180:183], v[224:227], v[24:27]
	v_mfma_f32_16x16x32_bf16 v[12:15], v[160:163], v[232:235], v[12:15]
	v_mfma_f32_16x16x32_bf16 v[8:11], v[180:183], v[232:235], v[8:11]
	s_setprio 0
	s_setprio 1
	v_mfma_f32_16x16x32_bf16 v[52:55], v[184:187], v[204:207], v[52:55]
	v_mfma_f32_16x16x32_bf16 v[48:51], v[192:195], v[204:207], v[48:51]
	v_mfma_f32_16x16x32_bf16 v[36:39], v[184:187], v[212:215], v[36:39]
	v_mfma_f32_16x16x32_bf16 v[32:35], v[192:195], v[212:215], v[32:35]
	v_mfma_f32_16x16x32_bf16 v[20:23], v[184:187], v[220:223], v[20:23]
	v_mfma_f32_16x16x32_bf16 v[16:19], v[192:195], v[220:223], v[16:19]
	v_mfma_f32_16x16x32_bf16 v[4:7], v[184:187], v[228:231], v[4:7]
	v_mfma_f32_16x16x32_bf16 v[0:3], v[192:195], v[228:231], v[0:3]
	v_mfma_f32_16x16x32_bf16 v[52:55], v[188:191], v[208:211], v[52:55]
	v_mfma_f32_16x16x32_bf16 v[48:51], v[196:199], v[208:211], v[48:51]
	v_mfma_f32_16x16x32_bf16 v[36:39], v[188:191], v[216:219], v[36:39]
	v_mfma_f32_16x16x32_bf16 v[32:35], v[196:199], v[216:219], v[32:35]
	v_mfma_f32_16x16x32_bf16 v[20:23], v[188:191], v[224:227], v[20:23]
	v_mfma_f32_16x16x32_bf16 v[16:19], v[196:199], v[224:227], v[16:19]
	v_mfma_f32_16x16x32_bf16 v[4:7], v[188:191], v[232:235], v[4:7]
	v_mfma_f32_16x16x32_bf16 v[0:3], v[196:199], v[232:235], v[0:3]
	s_setprio 0
	s_barrier
	s_add_i32 s36, 0, 0x18000
	v_add_u32_e32 v132, s36, v137
	s_add_i32 s100, 0, 0x1c000
	ds_read_b128 v[156:159], v132
	ds_read_b128 v[160:163], v132 offset:1024
	ds_read_b128 v[164:167], v132 offset:2048
	ds_read_b128 v[180:183], v132 offset:3072
	v_add_u32_e32 v132, s100, v137
	ds_read_b128 v[184:187], v132
	ds_read_b128 v[188:191], v132 offset:1024
	ds_read_b128 v[192:195], v132 offset:2048
	ds_read_b128 v[196:199], v132 offset:3072
	s_mov_b32 m0, s20
	ds_read_b128 v[204:207], v141 offset:32768
	ds_read_b128 v[208:211], v141 offset:33792
	ds_read_b128 v[212:215], v141 offset:34816
	ds_read_b128 v[216:219], v141 offset:35840
	ds_read_b128 v[220:223], v141 offset:36864
	ds_read_b128 v[224:227], v141 offset:37888
	ds_read_b128 v[228:231], v141 offset:38912
	ds_read_b128 v[232:235], v141 offset:39936
	global_load_lds_dwordx4 v251, s[72:73]
	s_mov_b32 m0, s21
	s_nop 0
	global_load_lds_dwordx4 v154, s[72:73]
	s_waitcnt vmcnt(8)
	s_waitcnt lgkmcnt(0)
	s_barrier
	s_setprio 1
	s_waitcnt lgkmcnt(0)
	v_mfma_f32_16x16x32_bf16 v[124:127], v[156:159], v[204:207], v[124:127]
	v_mfma_f32_16x16x32_bf16 v[120:123], v[164:167], v[204:207], v[120:123]
	v_mfma_f32_16x16x32_bf16 v[108:111], v[156:159], v[212:215], v[108:111]
	v_mfma_f32_16x16x32_bf16 v[104:107], v[164:167], v[212:215], v[104:107]
	v_mfma_f32_16x16x32_bf16 v[92:95], v[156:159], v[220:223], v[92:95]
	v_mfma_f32_16x16x32_bf16 v[88:91], v[164:167], v[220:223], v[88:91]
	v_mfma_f32_16x16x32_bf16 v[76:79], v[156:159], v[228:231], v[76:79]
	v_mfma_f32_16x16x32_bf16 v[72:75], v[164:167], v[228:231], v[72:75]
	v_mfma_f32_16x16x32_bf16 v[124:127], v[160:163], v[208:211], v[124:127]
	v_mfma_f32_16x16x32_bf16 v[120:123], v[180:183], v[208:211], v[120:123]
	v_mfma_f32_16x16x32_bf16 v[108:111], v[160:163], v[216:219], v[108:111]
	v_mfma_f32_16x16x32_bf16 v[104:107], v[180:183], v[216:219], v[104:107]
	v_mfma_f32_16x16x32_bf16 v[92:95], v[160:163], v[224:227], v[92:95]
	v_mfma_f32_16x16x32_bf16 v[88:91], v[180:183], v[224:227], v[88:91]
	v_mfma_f32_16x16x32_bf16 v[76:79], v[160:163], v[232:235], v[76:79]
	v_mfma_f32_16x16x32_bf16 v[72:75], v[180:183], v[232:235], v[72:75]
	s_setprio 0
	s_setprio 1
	v_mfma_f32_16x16x32_bf16 v[116:119], v[184:187], v[204:207], v[116:119]
	v_mfma_f32_16x16x32_bf16 v[112:115], v[192:195], v[204:207], v[112:115]
	v_mfma_f32_16x16x32_bf16 v[100:103], v[184:187], v[212:215], v[100:103]
	v_mfma_f32_16x16x32_bf16 v[96:99], v[192:195], v[212:215], v[96:99]
	v_mfma_f32_16x16x32_bf16 v[84:87], v[184:187], v[220:223], v[84:87]
	v_mfma_f32_16x16x32_bf16 v[80:83], v[192:195], v[220:223], v[80:83]
	v_mfma_f32_16x16x32_bf16 v[68:71], v[184:187], v[228:231], v[68:71]
	v_mfma_f32_16x16x32_bf16 v[64:67], v[192:195], v[228:231], v[64:67]
	v_mfma_f32_16x16x32_bf16 v[116:119], v[188:191], v[208:211], v[116:119]
	v_mfma_f32_16x16x32_bf16 v[112:115], v[196:199], v[208:211], v[112:115]
	v_mfma_f32_16x16x32_bf16 v[100:103], v[188:191], v[216:219], v[100:103]
	v_mfma_f32_16x16x32_bf16 v[96:99], v[196:199], v[216:219], v[96:99]
	v_mfma_f32_16x16x32_bf16 v[84:87], v[188:191], v[224:227], v[84:87]
	v_mfma_f32_16x16x32_bf16 v[80:83], v[196:199], v[224:227], v[80:83]
	v_mfma_f32_16x16x32_bf16 v[68:71], v[188:191], v[232:235], v[68:71]
	v_mfma_f32_16x16x32_bf16 v[64:67], v[196:199], v[232:235], v[64:67]
	s_setprio 0
	s_barrier
	s_add_i32 s36, s36, s17
	s_mov_b32 m0, s36
	ds_read_b128 v[204:207], v141 offset:49152
	ds_read_b128 v[208:211], v141 offset:50176
	ds_read_b128 v[212:215], v141 offset:51200
	ds_read_b128 v[216:219], v141 offset:52224
	ds_read_b128 v[220:223], v141 offset:53248
	ds_read_b128 v[224:227], v141 offset:54272
	ds_read_b128 v[228:231], v141 offset:55296
	ds_read_b128 v[232:235], v141 offset:56320
	global_load_lds_dwordx4 v155, s[86:87]
	s_add_i32 m0, s36, 0x2000
	s_add_i32 s36, s100, s17
	global_load_lds_dwordx4 v174, s[86:87]
	s_mov_b32 m0, s36
	s_nop 0
	global_load_lds_dwordx4 v175, s[86:87]
	s_add_i32 m0, s36, 0x2000
	s_nop 0
	global_load_lds_dwordx4 v176, s[86:87]
	s_mov_b32 m0, s22
	s_nop 0
	global_load_lds_dwordx4 v177, s[72:73]
	s_mov_b32 m0, s23
	s_nop 0
	global_load_lds_dwordx4 v149, s[72:73]
	s_waitcnt vmcnt(8)
	s_waitcnt lgkmcnt(0)
	s_barrier
	s_setprio 1
	s_waitcnt lgkmcnt(0)
	v_mfma_f32_16x16x32_bf16 v[60:63], v[156:159], v[204:207], v[60:63]
	v_mfma_f32_16x16x32_bf16 v[56:59], v[164:167], v[204:207], v[56:59]
	v_mfma_f32_16x16x32_bf16 v[44:47], v[156:159], v[212:215], v[44:47]
	v_mfma_f32_16x16x32_bf16 v[40:43], v[164:167], v[212:215], v[40:43]
	v_mfma_f32_16x16x32_bf16 v[28:31], v[156:159], v[220:223], v[28:31]
	v_mfma_f32_16x16x32_bf16 v[24:27], v[164:167], v[220:223], v[24:27]
	v_mfma_f32_16x16x32_bf16 v[12:15], v[156:159], v[228:231], v[12:15]
	v_mfma_f32_16x16x32_bf16 v[8:11], v[164:167], v[228:231], v[8:11]
	v_mfma_f32_16x16x32_bf16 v[60:63], v[160:163], v[208:211], v[60:63]
	v_mfma_f32_16x16x32_bf16 v[56:59], v[180:183], v[208:211], v[56:59]
	v_mfma_f32_16x16x32_bf16 v[44:47], v[160:163], v[216:219], v[44:47]
	v_mfma_f32_16x16x32_bf16 v[40:43], v[180:183], v[216:219], v[40:43]
	v_mfma_f32_16x16x32_bf16 v[28:31], v[160:163], v[224:227], v[28:31]
	v_mfma_f32_16x16x32_bf16 v[24:27], v[180:183], v[224:227], v[24:27]
	v_mfma_f32_16x16x32_bf16 v[12:15], v[160:163], v[232:235], v[12:15]
	v_mfma_f32_16x16x32_bf16 v[8:11], v[180:183], v[232:235], v[8:11]
	s_setprio 0
	s_setprio 1
	v_mfma_f32_16x16x32_bf16 v[52:55], v[184:187], v[204:207], v[52:55]
	v_mfma_f32_16x16x32_bf16 v[48:51], v[192:195], v[204:207], v[48:51]
	v_mfma_f32_16x16x32_bf16 v[36:39], v[184:187], v[212:215], v[36:39]
	v_mfma_f32_16x16x32_bf16 v[32:35], v[192:195], v[212:215], v[32:35]
	v_mfma_f32_16x16x32_bf16 v[20:23], v[184:187], v[220:223], v[20:23]
	v_mfma_f32_16x16x32_bf16 v[16:19], v[192:195], v[220:223], v[16:19]
	v_mfma_f32_16x16x32_bf16 v[4:7], v[184:187], v[228:231], v[4:7]
	v_mfma_f32_16x16x32_bf16 v[0:3], v[192:195], v[228:231], v[0:3]
	v_mfma_f32_16x16x32_bf16 v[52:55], v[188:191], v[208:211], v[52:55]
	v_mfma_f32_16x16x32_bf16 v[48:51], v[196:199], v[208:211], v[48:51]
	v_mfma_f32_16x16x32_bf16 v[36:39], v[188:191], v[216:219], v[36:39]
	v_mfma_f32_16x16x32_bf16 v[32:35], v[196:199], v[216:219], v[32:35]
	v_mfma_f32_16x16x32_bf16 v[20:23], v[188:191], v[224:227], v[20:23]
	v_mfma_f32_16x16x32_bf16 v[16:19], v[196:199], v[224:227], v[16:19]
	v_mfma_f32_16x16x32_bf16 v[4:7], v[188:191], v[232:235], v[4:7]
	v_mfma_f32_16x16x32_bf16 v[0:3], v[196:199], v[232:235], v[0:3]
	s_setprio 0
	s_barrier
	s_add_i32 s81, s81, 2
	s_add_u32 s70, s70, 0x100
	s_addc_u32 s71, s71, 0
	s_add_u32 s75, s75, 0x100
	s_addc_u32 s77, s77, 0
	s_cmp_gt_u32 s81, 61
	s_cbranch_scc0 .LBB0_333
	s_and_b64 vcc, exec, s[4:5]
	s_movk_i32 s77, 0x7fff
	s_cbranch_vccz .LBB0_336
	s_barrier
